# CDIL loop: four trips per pass (28 loads in flight per lane), weighted ADIFF spacing
# baseline (speedup 1.0000x reference)
; __device__ __forceinline__ int tid_opaque() { int t = threadIdx.x; asm volatile("" : "+v"(t)); return t; }
; __device__ __forceinline__ void dil_combine_phase(const Params& p, int half) {
;     ...
;     for (int idx = blockIdx.x * 512 + tid_opaque(); idx < 16384 * 128; idx += nth) {
;         const int row = idx >> 7, e = (idx & 127) * 8, h = e >> 7;
;         const float l0 = LSE[(size_t)row * 8 + h], l1 = LSE[(size_t)(16384 + row) * 8 + h], l2 = LSE[(size_t)(32768 + row) * 8 + h];
;         const float mx = fmaxf(l0, fmaxf(l1, l2)); float w0 = __builtin_amdgcn_exp2f(l0 - mx), w1 = __builtin_amdgcn_exp2f(l1 - mx), w2 = __builtin_amdgcn_exp2f(l2 - mx);
;         const float inv = 1.0f / (w0 + w1 + w2); w0 *= inv; w1 *= inv; w2 *= inv;
;         const u32x4 a = *(const u32x4*)(OG + (size_t)row * DM + e), b = *(const u32x4*)(OG + (size_t)(16384 + row) * DM + e), c = *(const u32x4*)(OG + (size_t)(32768 + row) * DM + e);
;         const u32x4 z = *(const u32x4*)(PROJ + (size_t)row * 8192 + 7168 + e);
.LBB0_68:
	v_ashrrev_i32_e32 v20, 7, v1
	v_ashrrev_i32_e32 v21, 31, v20
	v_lshlrev_b64 v[2:3], 5, v[20:21]
	v_lshrrev_b32_e32 v4, 5, v7
	v_lshl_add_u64 v[2:3], s[58:59], 0, v[2:3]
	v_and_b32_e32 v4, 28, v4
	v_mov_b32_e32 v5, v0
	v_add_u32_e32 v12, 0x4000, v20
	v_lshl_add_u64 v[2:3], v[2:3], 0, v[4:5]
	v_ashrrev_i32_e32 v13, 31, v12
	global_load_dword v6, v[2:3], off
	v_lshlrev_b64 v[2:3], 5, v[12:13]
	v_lshl_add_u64 v[2:3], s[58:59], 0, v[2:3]
	v_add_u32_e32 v16, 0x8000, v20
	v_lshl_add_u64 v[2:3], v[2:3], 0, v[4:5]
	v_ashrrev_i32_e32 v17, 31, v16
	global_load_dword v42, v[2:3], off
	v_lshlrev_b64 v[2:3], 5, v[16:17]
	v_lshl_add_u64 v[2:3], s[58:59], 0, v[2:3]
	v_lshl_add_u64 v[2:3], v[2:3], 0, v[4:5]
	global_load_dword v2, v[2:3], off
	v_and_b32_e32 v10, 0x3f8, v7
	v_lshlrev_b64 v[16:17], 11, v[16:17]
	s_mov_b32 s2, 0xd603000
	v_lshl_add_u64 v[16:17], s[90:91], 0, v[16:17]
	v_lshlrev_b64 v[12:13], 11, v[12:13]
	v_lshl_add_u64 v[12:13], s[90:91], 0, v[12:13]
	v_add_u32_e32 v1, s64, v1
	v_lshlrev_b64 v[36:37], 11, v[20:21]
	v_lshlrev_b64 v[20:21], 14, v[20:21]
	v_lshlrev_b32_e32 v38, 1, v10
	v_mov_b32_e32 v39, v0
	v_lshl_add_u64 v[20:21], s[68:69], 0, v[20:21]
	v_lshl_add_u64 v[20:21], v[20:21], 0, v[38:39]
	v_add_co_u32_e32 v20, vcc, s2, v20
	v_lshl_add_u64 v[8:9], s[90:91], 0, v[36:37]
	v_lshl_add_u64 v[16:17], v[16:17], 0, v[38:39]
	v_addc_co_u32_e32 v21, vcc, 0, v21, vcc
	v_lshl_add_u64 v[8:9], v[8:9], 0, v[38:39]
	global_load_dwordx4 v[16:19], v[16:17], off
	v_lshl_add_u64 v[12:13], v[12:13], 0, v[38:39]
	global_load_dwordx4 v[20:23], v[20:21], off offset:2048
	global_load_dwordx4 v[8:11], v[8:9], off
	global_load_dwordx4 v[12:15], v[12:13], off
	v_add_u32_e32 v7, s73, v7
	v_ashrrev_i32_e32 v68, 7, v1
	v_ashrrev_i32_e32 v69, 31, v68
	v_lshlrev_b64 v[50:51], 5, v[68:69]
	v_lshrrev_b32_e32 v52, 5, v7
	v_lshl_add_u64 v[50:51], s[58:59], 0, v[50:51]
	v_and_b32_e32 v52, 28, v52
	v_mov_b32_e32 v53, v0
	v_add_u32_e32 v60, 0x4000, v68
	v_lshl_add_u64 v[50:51], v[50:51], 0, v[52:53]
	v_ashrrev_i32_e32 v61, 31, v60
	global_load_dword v54, v[50:51], off
	v_lshlrev_b64 v[50:51], 5, v[60:61]
	v_lshl_add_u64 v[50:51], s[58:59], 0, v[50:51]
	v_add_u32_e32 v64, 0x8000, v68
	v_lshl_add_u64 v[50:51], v[50:51], 0, v[52:53]
	v_ashrrev_i32_e32 v65, 31, v64
	global_load_dword v90, v[50:51], off
	v_lshlrev_b64 v[50:51], 5, v[64:65]
	v_lshl_add_u64 v[50:51], s[58:59], 0, v[50:51]
	v_lshl_add_u64 v[50:51], v[50:51], 0, v[52:53]
	global_load_dword v50, v[50:51], off
	v_and_b32_e32 v58, 0x3f8, v7
	v_lshlrev_b64 v[64:65], 11, v[64:65]
	s_mov_b32 s2, 0xd603000
	v_lshl_add_u64 v[64:65], s[90:91], 0, v[64:65]
	v_lshlrev_b64 v[60:61], 11, v[60:61]
	v_lshl_add_u64 v[60:61], s[90:91], 0, v[60:61]
	v_add_u32_e32 v1, s64, v1
	v_lshlrev_b64 v[84:85], 11, v[68:69]
	v_lshlrev_b64 v[68:69], 14, v[68:69]
	v_lshlrev_b32_e32 v86, 1, v58
	v_mov_b32_e32 v87, v0
	v_lshl_add_u64 v[68:69], s[68:69], 0, v[68:69]
	v_lshl_add_u64 v[68:69], v[68:69], 0, v[86:87]
	v_add_co_u32_e32 v68, vcc, s2, v68
	v_lshl_add_u64 v[56:57], s[90:91], 0, v[84:85]
	v_lshl_add_u64 v[64:65], v[64:65], 0, v[86:87]
	v_addc_co_u32_e32 v69, vcc, 0, v69, vcc
	v_lshl_add_u64 v[56:57], v[56:57], 0, v[86:87]
	global_load_dwordx4 v[64:67], v[64:65], off
	v_lshl_add_u64 v[60:61], v[60:61], 0, v[86:87]
	global_load_dwordx4 v[68:71], v[68:69], off offset:2048
	global_load_dwordx4 v[56:59], v[56:57], off
	global_load_dwordx4 v[60:63], v[60:61], off
	v_add_u32_e32 v7, s73, v7
	v_ashrrev_i32_e32 v116, 7, v1
	v_ashrrev_i32_e32 v117, 31, v116
	v_lshlrev_b64 v[98:99], 5, v[116:117]
	v_lshrrev_b32_e32 v100, 5, v7
	v_lshl_add_u64 v[98:99], s[58:59], 0, v[98:99]
	v_and_b32_e32 v100, 28, v100
	v_mov_b32_e32 v101, v0
	v_add_u32_e32 v108, 0x4000, v116
	v_lshl_add_u64 v[98:99], v[98:99], 0, v[100:101]
	v_ashrrev_i32_e32 v109, 31, v108
	global_load_dword v102, v[98:99], off
	v_lshlrev_b64 v[98:99], 5, v[108:109]
	v_lshl_add_u64 v[98:99], s[58:59], 0, v[98:99]
	v_add_u32_e32 v112, 0x8000, v116
	v_lshl_add_u64 v[98:99], v[98:99], 0, v[100:101]
	v_ashrrev_i32_e32 v113, 31, v112
	global_load_dword v138, v[98:99], off
	v_lshlrev_b64 v[98:99], 5, v[112:113]
	v_lshl_add_u64 v[98:99], s[58:59], 0, v[98:99]
	v_lshl_add_u64 v[98:99], v[98:99], 0, v[100:101]
	global_load_dword v98, v[98:99], off
	v_and_b32_e32 v106, 0x3f8, v7
	v_lshlrev_b64 v[112:113], 11, v[112:113]
	s_mov_b32 s2, 0xd603000
	v_lshl_add_u64 v[112:113], s[90:91], 0, v[112:113]
	v_lshlrev_b64 v[108:109], 11, v[108:109]
	v_lshl_add_u64 v[108:109], s[90:91], 0, v[108:109]
	v_add_u32_e32 v1, s64, v1
	v_lshlrev_b64 v[132:133], 11, v[116:117]
	v_lshlrev_b64 v[116:117], 14, v[116:117]
	v_lshlrev_b32_e32 v134, 1, v106
	v_mov_b32_e32 v135, v0
	v_lshl_add_u64 v[116:117], s[68:69], 0, v[116:117]
	v_lshl_add_u64 v[116:117], v[116:117], 0, v[134:135]
	v_add_co_u32_e32 v116, vcc, s2, v116
	v_lshl_add_u64 v[104:105], s[90:91], 0, v[132:133]
	v_lshl_add_u64 v[112:113], v[112:113], 0, v[134:135]
	v_addc_co_u32_e32 v117, vcc, 0, v117, vcc
	v_lshl_add_u64 v[104:105], v[104:105], 0, v[134:135]
	global_load_dwordx4 v[112:115], v[112:113], off
	v_lshl_add_u64 v[108:109], v[108:109], 0, v[134:135]
	global_load_dwordx4 v[116:119], v[116:117], off offset:2048
	global_load_dwordx4 v[104:107], v[104:105], off
	global_load_dwordx4 v[108:111], v[108:109], off
	v_add_u32_e32 v7, s73, v7
	v_ashrrev_i32_e32 v164, 7, v1
	v_ashrrev_i32_e32 v165, 31, v164
	v_lshlrev_b64 v[146:147], 5, v[164:165]
	v_lshrrev_b32_e32 v148, 5, v7
	v_lshl_add_u64 v[146:147], s[58:59], 0, v[146:147]
	v_and_b32_e32 v148, 28, v148
	v_mov_b32_e32 v149, v0
	v_add_u32_e32 v156, 0x4000, v164
	v_lshl_add_u64 v[146:147], v[146:147], 0, v[148:149]
; __device__ __forceinline__ unsigned pk_bf16(float lo, float hi) { const f32x2 v = {lo, hi}; const bf16v2 b = __builtin_convertvector(v, bf16v2); return __builtin_bit_cast(unsigned, b); }
; __device__ __forceinline__ float bf_lo(unsigned u) { return __uint_as_float(u << 16); }
; __device__ __forceinline__ float bf_hi(unsigned u) { return __uint_as_float(u & 0xffff0000u); }
; __device__ __forceinline__ float silu_f(float v) { return v * __builtin_amdgcn_rcpf(1.0f + __builtin_amdgcn_exp2f(-LOG2E * v)); }
; __device__ __forceinline__ int tid_opaque() { int t = threadIdx.x; asm volatile("" : "+v"(t)); return t; }
; __device__ __forceinline__ void dil_combine_phase(const Params& p, int half) {
;     ...
;     for (int idx = blockIdx.x * 512 + tid_opaque(); idx < 16384 * 128; idx += nth) {
;         const int row = idx >> 7, e = (idx & 127) * 8, h = e >> 7;
;         const float l0 = LSE[(size_t)row * 8 + h], l1 = LSE[(size_t)(16384 + row) * 8 + h], l2 = LSE[(size_t)(32768 + row) * 8 + h];
;         const float mx = fmaxf(l0, fmaxf(l1, l2)); float w0 = __builtin_amdgcn_exp2f(l0 - mx), w1 = __builtin_amdgcn_exp2f(l1 - mx), w2 = __builtin_amdgcn_exp2f(l2 - mx);
;         const float inv = 1.0f / (w0 + w1 + w2); w0 *= inv; w1 *= inv; w2 *= inv;
;         const u32x4 a = *(const u32x4*)(OG + (size_t)row * DM + e), b = *(const u32x4*)(OG + (size_t)(16384 + row) * DM + e), c = *(const u32x4*)(OG + (size_t)(32768 + row) * DM + e);
;         const u32x4 z = *(const u32x4*)(PROJ + (size_t)row * 8192 + 7168 + e);
;         u32x4 o;
; #pragma unroll
;         for (int j = 0; j < 4; ++j) {
;             const float lo = (w0 * bf_lo(a[j]) + w1 * bf_lo(b[j]) + w2 * bf_lo(c[j])) * silu_f(bf_lo(z[j]));
;             const float hi = (w0 * bf_hi(a[j]) + w1 * bf_hi(b[j]) + w2 * bf_hi(c[j])) * silu_f(bf_hi(z[j]));
;             o[j] = pk_bf16(lo, hi);
;         }
;         *(u32x4*)(Y + (size_t)row * DM + e) = o;
	v_ashrrev_i32_e32 v157, 31, v156
	global_load_dword v150, v[146:147], off
	v_lshlrev_b64 v[146:147], 5, v[156:157]
	v_lshl_add_u64 v[146:147], s[58:59], 0, v[146:147]
	v_add_u32_e32 v160, 0x8000, v164
	v_lshl_add_u64 v[146:147], v[146:147], 0, v[148:149]
	v_ashrrev_i32_e32 v161, 31, v160
	global_load_dword v186, v[146:147], off
	v_lshlrev_b64 v[146:147], 5, v[160:161]
	v_lshl_add_u64 v[146:147], s[58:59], 0, v[146:147]
	v_lshl_add_u64 v[146:147], v[146:147], 0, v[148:149]
	global_load_dword v146, v[146:147], off
	v_and_b32_e32 v154, 0x3f8, v7
	v_lshlrev_b64 v[160:161], 11, v[160:161]
	s_mov_b32 s2, 0xd603000
	v_lshl_add_u64 v[160:161], s[90:91], 0, v[160:161]
	v_lshlrev_b64 v[156:157], 11, v[156:157]
	v_lshl_add_u64 v[156:157], s[90:91], 0, v[156:157]
	v_add_u32_e32 v1, s64, v1
	v_lshlrev_b64 v[180:181], 11, v[164:165]
	v_lshlrev_b64 v[164:165], 14, v[164:165]
	v_lshlrev_b32_e32 v182, 1, v154
	v_mov_b32_e32 v183, v0
	v_lshl_add_u64 v[164:165], s[68:69], 0, v[164:165]
	v_lshl_add_u64 v[164:165], v[164:165], 0, v[182:183]
	v_add_co_u32_e32 v164, vcc, s2, v164
	v_lshl_add_u64 v[152:153], s[90:91], 0, v[180:181]
	v_lshl_add_u64 v[160:161], v[160:161], 0, v[182:183]
	v_addc_co_u32_e32 v165, vcc, 0, v165, vcc
	v_lshl_add_u64 v[152:153], v[152:153], 0, v[182:183]
	global_load_dwordx4 v[160:163], v[160:161], off
	v_lshl_add_u64 v[156:157], v[156:157], 0, v[182:183]
	global_load_dwordx4 v[164:167], v[164:165], off offset:2048
	global_load_dwordx4 v[152:155], v[152:153], off
	global_load_dwordx4 v[156:159], v[156:157], off
	v_add_u32_e32 v7, s73, v7
	s_waitcnt vmcnt(25)
	v_max3_f32 v3, v6, v42, v2
	v_sub_f32_e32 v4, v6, v3
	v_exp_f32_e32 v25, v4
	v_sub_f32_e32 v4, v42, v3
	v_exp_f32_e32 v24, v4
	v_sub_f32_e32 v2, v2, v3
	v_exp_f32_e32 v2, v2
	v_add_f32_e32 v3, v25, v24
	v_add_f32_e32 v3, v2, v3
	v_div_scale_f32 v4, s[4:5], v3, v3, 1.0
	v_rcp_f32_e32 v5, v4
	s_nop 0
	v_fma_f32 v6, -v4, v5, 1.0
	v_fmac_f32_e32 v5, v6, v5
	v_div_scale_f32 v6, vcc, 1.0, v3, 1.0
	v_mul_f32_e32 v42, v6, v5
	v_fma_f32 v43, -v4, v42, v6
	v_fmac_f32_e32 v42, v43, v5
	v_fma_f32 v4, -v4, v42, v6
	v_div_fmas_f32 v4, v4, v5, v42
	v_div_fixup_f32 v26, v4, v3, 1.0
	v_mul_f32_e32 v6, v2, v26
	v_pk_mul_f32 v[24:25], v[24:25], v[26:27] op_sel_hi:[1,0]
	s_mov_b32 s2, 0x1fffff
	v_lshl_add_u64 v[2:3], s[40:41], 0, v[36:37]
	v_cmp_lt_i32_e32 vcc, s2, v1
	v_lshl_add_u64 v[2:3], v[2:3], 0, v[38:39]
	s_or_b64 s[42:43], vcc, s[42:43]
	s_waitcnt vmcnt(24)
	v_lshlrev_b32_e32 v34, 16, v16
	v_and_b32_e32 v35, 0xffff0000, v16
	s_waitcnt vmcnt(23)
	v_lshlrev_b32_e32 v26, 16, v20
	v_and_b32_e32 v27, 0xffff0000, v20
	v_mul_f32_e32 v20, 0xbfb8aa3b, v26
	s_waitcnt vmcnt(22)
	v_and_b32_e32 v31, 0xffff0000, v8
	v_lshlrev_b32_e32 v32, 16, v8
	v_mul_f32_e32 v8, 0xbfb8aa3b, v27
	v_exp_f32_e32 v20, v20
	v_exp_f32_e32 v8, v8
	s_waitcnt vmcnt(21)
	v_and_b32_e32 v33, 0xffff0000, v12
	v_lshlrev_b32_e32 v30, 16, v12
	v_add_f32_e32 v20, 1.0, v20
	v_add_f32_e32 v8, 1.0, v8
	v_rcp_f32_e32 v28, v20
	v_rcp_f32_e32 v29, v8
	v_lshlrev_b32_e32 v20, 16, v21
	v_and_b32_e32 v21, 0xffff0000, v21
	v_mul_f32_e32 v12, 0xbfb8aa3b, v20
	v_pk_mul_f32 v[26:27], v[28:29], v[26:27]
	v_pk_mul_f32 v[28:29], v[24:25], v[32:33] op_sel:[1,0] op_sel_hi:[0,1]
	v_pk_fma_f32 v[28:29], v[24:25], v[30:31], v[28:29]
	v_exp_f32_e32 v12, v12
	v_pk_fma_f32 v[28:29], v[6:7], v[34:35], v[28:29] op_sel_hi:[0,1,1]
	v_pk_mul_f32 v[26:27], v[28:29], v[26:27]
	v_lshlrev_b32_e32 v28, 16, v9
	v_cvt_pk_bf16_f32 v8, v26, v27
	v_and_b32_e32 v27, 0xffff0000, v9
	v_mul_f32_e32 v9, 0xbfb8aa3b, v21
	v_exp_f32_e32 v9, v9
	v_add_f32_e32 v12, 1.0, v12
	v_rcp_f32_e32 v12, v12
	v_lshlrev_b32_e32 v26, 16, v13
	v_add_f32_e32 v9, 1.0, v9
	v_and_b32_e32 v29, 0xffff0000, v13
	v_rcp_f32_e32 v13, v9
	v_lshlrev_b32_e32 v16, 16, v17
	v_and_b32_e32 v17, 0xffff0000, v17
	v_pk_mul_f32 v[12:13], v[12:13], v[20:21]
	v_pk_mul_f32 v[20:21], v[24:25], v[28:29] op_sel:[1,0] op_sel_hi:[0,1]
	v_pk_fma_f32 v[20:21], v[24:25], v[26:27], v[20:21]
	v_lshlrev_b32_e32 v26, 16, v10
	v_pk_fma_f32 v[16:17], v[6:7], v[16:17], v[20:21] op_sel_hi:[0,1,1]
	v_pk_mul_f32 v[12:13], v[16:17], v[12:13]
	v_and_b32_e32 v21, 0xffff0000, v10
	v_cvt_pk_bf16_f32 v9, v12, v13
	v_lshlrev_b32_e32 v12, 16, v22
	v_and_b32_e32 v13, 0xffff0000, v22
	v_mul_f32_e32 v16, 0xbfb8aa3b, v12
	v_mul_f32_e32 v10, 0xbfb8aa3b, v13
	v_exp_f32_e32 v16, v16
	v_exp_f32_e32 v10, v10
	v_and_b32_e32 v27, 0xffff0000, v14
	v_lshlrev_b32_e32 v20, 16, v14
	v_add_f32_e32 v16, 1.0, v16
	v_add_f32_e32 v10, 1.0, v10
	v_rcp_f32_e32 v16, v16
	v_rcp_f32_e32 v17, v10
	v_lshlrev_b32_e32 v28, 16, v18
	v_and_b32_e32 v29, 0xffff0000, v18
	v_lshlrev_b32_e32 v18, 16, v19
	v_pk_mul_f32 v[12:13], v[16:17], v[12:13]
	v_pk_mul_f32 v[16:17], v[24:25], v[26:27] op_sel:[1,0] op_sel_hi:[0,1]
	v_pk_fma_f32 v[16:17], v[24:25], v[20:21], v[16:17]
	v_lshlrev_b32_e32 v20, 16, v11
	v_pk_fma_f32 v[16:17], v[6:7], v[28:29], v[16:17] op_sel_hi:[0,1,1]
	v_and_b32_e32 v21, 0xffff0000, v15
	v_pk_mul_f32 v[12:13], v[16:17], v[12:13]
	v_lshlrev_b32_e32 v16, 16, v15
	v_and_b32_e32 v17, 0xffff0000, v11
	v_pk_mul_f32 v[20:21], v[24:25], v[20:21] op_sel:[1,0] op_sel_hi:[0,1]
	v_cvt_pk_bf16_f32 v10, v12, v13
	v_lshlrev_b32_e32 v12, 16, v23
	v_and_b32_e32 v13, 0xffff0000, v23
	v_pk_fma_f32 v[16:17], v[24:25], v[16:17], v[20:21]
	v_and_b32_e32 v19, 0xffff0000, v19
	v_mul_f32_e32 v14, 0xbfb8aa3b, v12
	v_pk_fma_f32 v[16:17], v[6:7], v[18:19], v[16:17] op_sel_hi:[0,1,1]
	v_mul_f32_e32 v6, 0xbfb8aa3b, v13
	v_exp_f32_e32 v14, v14
	v_exp_f32_e32 v6, v6
	v_add_f32_e32 v14, 1.0, v14
	v_add_f32_e32 v6, 1.0, v6
	v_rcp_f32_e32 v14, v14
	v_rcp_f32_e32 v15, v6
	s_nop 0
	v_pk_mul_f32 v[12:13], v[14:15], v[12:13]
	s_nop 0
	v_pk_mul_f32 v[12:13], v[16:17], v[12:13]
	s_nop 0
	v_cvt_pk_bf16_f32 v11, v12, v13
	global_store_dwordx4 v[2:3], v[8:11], off
	s_waitcnt vmcnt(19)
; __device__ __forceinline__ unsigned pk_bf16(float lo, float hi) { const f32x2 v = {lo, hi}; const bf16v2 b = __builtin_convertvector(v, bf16v2); return __builtin_bit_cast(unsigned, b); }
; __device__ __forceinline__ float bf_lo(unsigned u) { return __uint_as_float(u << 16); }
; __device__ __forceinline__ float bf_hi(unsigned u) { return __uint_as_float(u & 0xffff0000u); }
; __device__ __forceinline__ float silu_f(float v) { return v * __builtin_amdgcn_rcpf(1.0f + __builtin_amdgcn_exp2f(-LOG2E * v)); }
; __device__ __forceinline__ int tid_opaque() { int t = threadIdx.x; asm volatile("" : "+v"(t)); return t; }
; __device__ __forceinline__ void dil_combine_phase(const Params& p, int half) {
;     ...
;     for (int idx = blockIdx.x * 512 + tid_opaque(); idx < 16384 * 128; idx += nth) {
;         const int row = idx >> 7, e = (idx & 127) * 8, h = e >> 7;
;         const float l0 = LSE[(size_t)row * 8 + h], l1 = LSE[(size_t)(16384 + row) * 8 + h], l2 = LSE[(size_t)(32768 + row) * 8 + h];
;         const float mx = fmaxf(l0, fmaxf(l1, l2)); float w0 = __builtin_amdgcn_exp2f(l0 - mx), w1 = __builtin_amdgcn_exp2f(l1 - mx), w2 = __builtin_amdgcn_exp2f(l2 - mx);
;         const float inv = 1.0f / (w0 + w1 + w2); w0 *= inv; w1 *= inv; w2 *= inv;
;         const u32x4 a = *(const u32x4*)(OG + (size_t)row * DM + e), b = *(const u32x4*)(OG + (size_t)(16384 + row) * DM + e), c = *(const u32x4*)(OG + (size_t)(32768 + row) * DM + e);
;         const u32x4 z = *(const u32x4*)(PROJ + (size_t)row * 8192 + 7168 + e);
;         u32x4 o;
; #pragma unroll
;         for (int j = 0; j < 4; ++j) {
;             const float lo = (w0 * bf_lo(a[j]) + w1 * bf_lo(b[j]) + w2 * bf_lo(c[j])) * silu_f(bf_lo(z[j]));
;             const float hi = (w0 * bf_hi(a[j]) + w1 * bf_hi(b[j]) + w2 * bf_hi(c[j])) * silu_f(bf_hi(z[j]));
;             o[j] = pk_bf16(lo, hi);
;         }
;         *(u32x4*)(Y + (size_t)row * DM + e) = o;
	v_max3_f32 v51, v54, v90, v50
	v_sub_f32_e32 v52, v54, v51
	v_exp_f32_e32 v73, v52
	v_sub_f32_e32 v52, v90, v51
	v_exp_f32_e32 v72, v52
	v_sub_f32_e32 v50, v50, v51
	v_exp_f32_e32 v50, v50
	v_add_f32_e32 v51, v73, v72
	v_add_f32_e32 v51, v50, v51
	v_div_scale_f32 v52, s[4:5], v51, v51, 1.0
	v_rcp_f32_e32 v53, v52
	s_nop 0
	v_fma_f32 v54, -v52, v53, 1.0
	v_fmac_f32_e32 v53, v54, v53
	v_div_scale_f32 v54, vcc, 1.0, v51, 1.0
	v_mul_f32_e32 v90, v54, v53
	v_fma_f32 v91, -v52, v90, v54
	v_fmac_f32_e32 v90, v91, v53
	v_fma_f32 v52, -v52, v90, v54
	v_div_fmas_f32 v52, v52, v53, v90
	v_div_fixup_f32 v74, v52, v51, 1.0
	v_mul_f32_e32 v54, v50, v74
	v_pk_mul_f32 v[72:73], v[72:73], v[74:75] op_sel_hi:[1,0]
	s_mov_b32 s2, 0x1fffff
	v_lshl_add_u64 v[50:51], s[40:41], 0, v[84:85]
	v_cmp_lt_i32_e32 vcc, s2, v1
	v_lshl_add_u64 v[50:51], v[50:51], 0, v[86:87]
	s_or_b64 s[42:43], vcc, s[42:43]
	s_waitcnt vmcnt(18)
	v_lshlrev_b32_e32 v82, 16, v64
	v_and_b32_e32 v83, 0xffff0000, v64
	s_waitcnt vmcnt(17)
	v_lshlrev_b32_e32 v74, 16, v68
	v_and_b32_e32 v75, 0xffff0000, v68
	v_mul_f32_e32 v68, 0xbfb8aa3b, v74
	s_waitcnt vmcnt(16)
	v_and_b32_e32 v79, 0xffff0000, v56
	v_lshlrev_b32_e32 v80, 16, v56
	v_mul_f32_e32 v56, 0xbfb8aa3b, v75
	v_exp_f32_e32 v68, v68
	v_exp_f32_e32 v56, v56
	s_waitcnt vmcnt(15)
	v_and_b32_e32 v81, 0xffff0000, v60
	v_lshlrev_b32_e32 v78, 16, v60
	v_add_f32_e32 v68, 1.0, v68
	v_add_f32_e32 v56, 1.0, v56
	v_rcp_f32_e32 v76, v68
	v_rcp_f32_e32 v77, v56
	v_lshlrev_b32_e32 v68, 16, v69
	v_and_b32_e32 v69, 0xffff0000, v69
	v_mul_f32_e32 v60, 0xbfb8aa3b, v68
	v_pk_mul_f32 v[74:75], v[76:77], v[74:75]
	v_pk_mul_f32 v[76:77], v[72:73], v[80:81] op_sel:[1,0] op_sel_hi:[0,1]
	v_pk_fma_f32 v[76:77], v[72:73], v[78:79], v[76:77]
	v_exp_f32_e32 v60, v60
	v_pk_fma_f32 v[76:77], v[54:55], v[82:83], v[76:77] op_sel_hi:[0,1,1]
	v_pk_mul_f32 v[74:75], v[76:77], v[74:75]
	v_lshlrev_b32_e32 v76, 16, v57
	v_cvt_pk_bf16_f32 v56, v74, v75
	v_and_b32_e32 v75, 0xffff0000, v57
	v_mul_f32_e32 v57, 0xbfb8aa3b, v69
	v_exp_f32_e32 v57, v57
	v_add_f32_e32 v60, 1.0, v60
	v_rcp_f32_e32 v60, v60
	v_lshlrev_b32_e32 v74, 16, v61
	v_add_f32_e32 v57, 1.0, v57
	v_and_b32_e32 v77, 0xffff0000, v61
	v_rcp_f32_e32 v61, v57
	v_lshlrev_b32_e32 v64, 16, v65
	v_and_b32_e32 v65, 0xffff0000, v65
	v_pk_mul_f32 v[60:61], v[60:61], v[68:69]
	v_pk_mul_f32 v[68:69], v[72:73], v[76:77] op_sel:[1,0] op_sel_hi:[0,1]
	v_pk_fma_f32 v[68:69], v[72:73], v[74:75], v[68:69]
	v_lshlrev_b32_e32 v74, 16, v58
	v_pk_fma_f32 v[64:65], v[54:55], v[64:65], v[68:69] op_sel_hi:[0,1,1]
	v_pk_mul_f32 v[60:61], v[64:65], v[60:61]
	v_and_b32_e32 v69, 0xffff0000, v58
	v_cvt_pk_bf16_f32 v57, v60, v61
	v_lshlrev_b32_e32 v60, 16, v70
	v_and_b32_e32 v61, 0xffff0000, v70
	v_mul_f32_e32 v64, 0xbfb8aa3b, v60
	v_mul_f32_e32 v58, 0xbfb8aa3b, v61
	v_exp_f32_e32 v64, v64
	v_exp_f32_e32 v58, v58
	v_and_b32_e32 v75, 0xffff0000, v62
	v_lshlrev_b32_e32 v68, 16, v62
	v_add_f32_e32 v64, 1.0, v64
	v_add_f32_e32 v58, 1.0, v58
	v_rcp_f32_e32 v64, v64
	v_rcp_f32_e32 v65, v58
	v_lshlrev_b32_e32 v76, 16, v66
	v_and_b32_e32 v77, 0xffff0000, v66
	v_lshlrev_b32_e32 v66, 16, v67
	v_pk_mul_f32 v[60:61], v[64:65], v[60:61]
	v_pk_mul_f32 v[64:65], v[72:73], v[74:75] op_sel:[1,0] op_sel_hi:[0,1]
	v_pk_fma_f32 v[64:65], v[72:73], v[68:69], v[64:65]
	v_lshlrev_b32_e32 v68, 16, v59
	v_pk_fma_f32 v[64:65], v[54:55], v[76:77], v[64:65] op_sel_hi:[0,1,1]
	v_and_b32_e32 v69, 0xffff0000, v63
	v_pk_mul_f32 v[60:61], v[64:65], v[60:61]
	v_lshlrev_b32_e32 v64, 16, v63
	v_and_b32_e32 v65, 0xffff0000, v59
	v_pk_mul_f32 v[68:69], v[72:73], v[68:69] op_sel:[1,0] op_sel_hi:[0,1]
	v_cvt_pk_bf16_f32 v58, v60, v61
	v_lshlrev_b32_e32 v60, 16, v71
	v_and_b32_e32 v61, 0xffff0000, v71
	v_pk_fma_f32 v[64:65], v[72:73], v[64:65], v[68:69]
	v_and_b32_e32 v67, 0xffff0000, v67
	v_mul_f32_e32 v62, 0xbfb8aa3b, v60
	v_pk_fma_f32 v[64:65], v[54:55], v[66:67], v[64:65] op_sel_hi:[0,1,1]
	v_mul_f32_e32 v54, 0xbfb8aa3b, v61
	v_exp_f32_e32 v62, v62
	v_exp_f32_e32 v54, v54
	v_add_f32_e32 v62, 1.0, v62
	v_add_f32_e32 v54, 1.0, v54
	v_rcp_f32_e32 v62, v62
	v_rcp_f32_e32 v63, v54
	s_nop 0
	v_pk_mul_f32 v[60:61], v[62:63], v[60:61]
	s_nop 0
	v_pk_mul_f32 v[60:61], v[64:65], v[60:61]
	s_nop 0
	v_cvt_pk_bf16_f32 v59, v60, v61
	global_store_dwordx4 v[50:51], v[56:59], off
	s_waitcnt vmcnt(13)
	v_max3_f32 v99, v102, v138, v98
	v_sub_f32_e32 v100, v102, v99
	v_exp_f32_e32 v121, v100
	v_sub_f32_e32 v100, v138, v99
	v_exp_f32_e32 v120, v100
	v_sub_f32_e32 v98, v98, v99
	v_exp_f32_e32 v98, v98
	v_add_f32_e32 v99, v121, v120
	v_add_f32_e32 v99, v98, v99
	v_div_scale_f32 v100, s[4:5], v99, v99, 1.0
	v_rcp_f32_e32 v101, v100
	s_nop 0
	v_fma_f32 v102, -v100, v101, 1.0
	v_fmac_f32_e32 v101, v102, v101
	v_div_scale_f32 v102, vcc, 1.0, v99, 1.0
	v_mul_f32_e32 v138, v102, v101
	v_fma_f32 v139, -v100, v138, v102
	v_fmac_f32_e32 v138, v139, v101
	v_fma_f32 v100, -v100, v138, v102
	v_div_fmas_f32 v100, v100, v101, v138
	v_div_fixup_f32 v122, v100, v99, 1.0
	v_mul_f32_e32 v102, v98, v122
	v_pk_mul_f32 v[120:121], v[120:121], v[122:123] op_sel_hi:[1,0]
	s_mov_b32 s2, 0x1fffff
	v_lshl_add_u64 v[98:99], s[40:41], 0, v[132:133]
	v_cmp_lt_i32_e32 vcc, s2, v1
	v_lshl_add_u64 v[98:99], v[98:99], 0, v[134:135]
	s_or_b64 s[42:43], vcc, s[42:43]
	s_waitcnt vmcnt(12)
	v_lshlrev_b32_e32 v130, 16, v112
	v_and_b32_e32 v131, 0xffff0000, v112
	s_waitcnt vmcnt(11)
	v_lshlrev_b32_e32 v122, 16, v116
	v_and_b32_e32 v123, 0xffff0000, v116
	v_mul_f32_e32 v116, 0xbfb8aa3b, v122
	s_waitcnt vmcnt(10)
	v_and_b32_e32 v127, 0xffff0000, v104
	v_lshlrev_b32_e32 v128, 16, v104
	v_mul_f32_e32 v104, 0xbfb8aa3b, v123
	v_exp_f32_e32 v116, v116
	v_exp_f32_e32 v104, v104
	s_waitcnt vmcnt(9)
; __device__ __forceinline__ unsigned pk_bf16(float lo, float hi) { const f32x2 v = {lo, hi}; const bf16v2 b = __builtin_convertvector(v, bf16v2); return __builtin_bit_cast(unsigned, b); }
; __device__ __forceinline__ float bf_lo(unsigned u) { return __uint_as_float(u << 16); }
; __device__ __forceinline__ float bf_hi(unsigned u) { return __uint_as_float(u & 0xffff0000u); }
; __device__ __forceinline__ float silu_f(float v) { return v * __builtin_amdgcn_rcpf(1.0f + __builtin_amdgcn_exp2f(-LOG2E * v)); }
; __device__ __forceinline__ int tid_opaque() { int t = threadIdx.x; asm volatile("" : "+v"(t)); return t; }
; __device__ __forceinline__ void dil_combine_phase(const Params& p, int half) {
;     ...
;     for (int idx = blockIdx.x * 512 + tid_opaque(); idx < 16384 * 128; idx += nth) {
;         const int row = idx >> 7, e = (idx & 127) * 8, h = e >> 7;
;         const float l0 = LSE[(size_t)row * 8 + h], l1 = LSE[(size_t)(16384 + row) * 8 + h], l2 = LSE[(size_t)(32768 + row) * 8 + h];
;         const float mx = fmaxf(l0, fmaxf(l1, l2)); float w0 = __builtin_amdgcn_exp2f(l0 - mx), w1 = __builtin_amdgcn_exp2f(l1 - mx), w2 = __builtin_amdgcn_exp2f(l2 - mx);
;         const float inv = 1.0f / (w0 + w1 + w2); w0 *= inv; w1 *= inv; w2 *= inv;
;         const u32x4 a = *(const u32x4*)(OG + (size_t)row * DM + e), b = *(const u32x4*)(OG + (size_t)(16384 + row) * DM + e), c = *(const u32x4*)(OG + (size_t)(32768 + row) * DM + e);
;         const u32x4 z = *(const u32x4*)(PROJ + (size_t)row * 8192 + 7168 + e);
;         u32x4 o;
; #pragma unroll
;         for (int j = 0; j < 4; ++j) {
;             const float lo = (w0 * bf_lo(a[j]) + w1 * bf_lo(b[j]) + w2 * bf_lo(c[j])) * silu_f(bf_lo(z[j]));
;             const float hi = (w0 * bf_hi(a[j]) + w1 * bf_hi(b[j]) + w2 * bf_hi(c[j])) * silu_f(bf_hi(z[j]));
;             o[j] = pk_bf16(lo, hi);
;         }
;         *(u32x4*)(Y + (size_t)row * DM + e) = o;
	v_and_b32_e32 v129, 0xffff0000, v108
	v_lshlrev_b32_e32 v126, 16, v108
	v_add_f32_e32 v116, 1.0, v116
	v_add_f32_e32 v104, 1.0, v104
	v_rcp_f32_e32 v124, v116
	v_rcp_f32_e32 v125, v104
	v_lshlrev_b32_e32 v116, 16, v117
	v_and_b32_e32 v117, 0xffff0000, v117
	v_mul_f32_e32 v108, 0xbfb8aa3b, v116
	v_pk_mul_f32 v[122:123], v[124:125], v[122:123]
	v_pk_mul_f32 v[124:125], v[120:121], v[128:129] op_sel:[1,0] op_sel_hi:[0,1]
	v_pk_fma_f32 v[124:125], v[120:121], v[126:127], v[124:125]
	v_exp_f32_e32 v108, v108
	v_pk_fma_f32 v[124:125], v[102:103], v[130:131], v[124:125] op_sel_hi:[0,1,1]
	v_pk_mul_f32 v[122:123], v[124:125], v[122:123]
	v_lshlrev_b32_e32 v124, 16, v105
	v_cvt_pk_bf16_f32 v104, v122, v123
	v_and_b32_e32 v123, 0xffff0000, v105
	v_mul_f32_e32 v105, 0xbfb8aa3b, v117
	v_exp_f32_e32 v105, v105
	v_add_f32_e32 v108, 1.0, v108
	v_rcp_f32_e32 v108, v108
	v_lshlrev_b32_e32 v122, 16, v109
	v_add_f32_e32 v105, 1.0, v105
	v_and_b32_e32 v125, 0xffff0000, v109
	v_rcp_f32_e32 v109, v105
	v_lshlrev_b32_e32 v112, 16, v113
	v_and_b32_e32 v113, 0xffff0000, v113
	v_pk_mul_f32 v[108:109], v[108:109], v[116:117]
	v_pk_mul_f32 v[116:117], v[120:121], v[124:125] op_sel:[1,0] op_sel_hi:[0,1]
	v_pk_fma_f32 v[116:117], v[120:121], v[122:123], v[116:117]
	v_lshlrev_b32_e32 v122, 16, v106
	v_pk_fma_f32 v[112:113], v[102:103], v[112:113], v[116:117] op_sel_hi:[0,1,1]
	v_pk_mul_f32 v[108:109], v[112:113], v[108:109]
	v_and_b32_e32 v117, 0xffff0000, v106
	v_cvt_pk_bf16_f32 v105, v108, v109
	v_lshlrev_b32_e32 v108, 16, v118
	v_and_b32_e32 v109, 0xffff0000, v118
	v_mul_f32_e32 v112, 0xbfb8aa3b, v108
	v_mul_f32_e32 v106, 0xbfb8aa3b, v109
	v_exp_f32_e32 v112, v112
	v_exp_f32_e32 v106, v106
	v_and_b32_e32 v123, 0xffff0000, v110
	v_lshlrev_b32_e32 v116, 16, v110
	v_add_f32_e32 v112, 1.0, v112
	v_add_f32_e32 v106, 1.0, v106
	v_rcp_f32_e32 v112, v112
	v_rcp_f32_e32 v113, v106
	v_lshlrev_b32_e32 v124, 16, v114
	v_and_b32_e32 v125, 0xffff0000, v114
	v_lshlrev_b32_e32 v114, 16, v115
	v_pk_mul_f32 v[108:109], v[112:113], v[108:109]
	v_pk_mul_f32 v[112:113], v[120:121], v[122:123] op_sel:[1,0] op_sel_hi:[0,1]
	v_pk_fma_f32 v[112:113], v[120:121], v[116:117], v[112:113]
	v_lshlrev_b32_e32 v116, 16, v107
	v_pk_fma_f32 v[112:113], v[102:103], v[124:125], v[112:113] op_sel_hi:[0,1,1]
	v_and_b32_e32 v117, 0xffff0000, v111
	v_pk_mul_f32 v[108:109], v[112:113], v[108:109]
	v_lshlrev_b32_e32 v112, 16, v111
	v_and_b32_e32 v113, 0xffff0000, v107
	v_pk_mul_f32 v[116:117], v[120:121], v[116:117] op_sel:[1,0] op_sel_hi:[0,1]
	v_cvt_pk_bf16_f32 v106, v108, v109
	v_lshlrev_b32_e32 v108, 16, v119
	v_and_b32_e32 v109, 0xffff0000, v119
	v_pk_fma_f32 v[112:113], v[120:121], v[112:113], v[116:117]
	v_and_b32_e32 v115, 0xffff0000, v115
	v_mul_f32_e32 v110, 0xbfb8aa3b, v108
	v_pk_fma_f32 v[112:113], v[102:103], v[114:115], v[112:113] op_sel_hi:[0,1,1]
	v_mul_f32_e32 v102, 0xbfb8aa3b, v109
	v_exp_f32_e32 v110, v110
	v_exp_f32_e32 v102, v102
	v_add_f32_e32 v110, 1.0, v110
	v_add_f32_e32 v102, 1.0, v102
	v_rcp_f32_e32 v110, v110
	v_rcp_f32_e32 v111, v102
	s_nop 0
	v_pk_mul_f32 v[108:109], v[110:111], v[108:109]
	s_nop 0
	v_pk_mul_f32 v[108:109], v[112:113], v[108:109]
	s_nop 0
	v_cvt_pk_bf16_f32 v107, v108, v109
	global_store_dwordx4 v[98:99], v[104:107], off
	s_waitcnt vmcnt(7)
	v_max3_f32 v147, v150, v186, v146
	v_sub_f32_e32 v148, v150, v147
	v_exp_f32_e32 v169, v148
	v_sub_f32_e32 v148, v186, v147
	v_exp_f32_e32 v168, v148
	v_sub_f32_e32 v146, v146, v147
	v_exp_f32_e32 v146, v146
	v_add_f32_e32 v147, v169, v168
	v_add_f32_e32 v147, v146, v147
	v_div_scale_f32 v148, s[4:5], v147, v147, 1.0
	v_rcp_f32_e32 v149, v148
	s_nop 0
	v_fma_f32 v150, -v148, v149, 1.0
	v_fmac_f32_e32 v149, v150, v149
	v_div_scale_f32 v150, vcc, 1.0, v147, 1.0
	v_mul_f32_e32 v186, v150, v149
	v_fma_f32 v187, -v148, v186, v150
	v_fmac_f32_e32 v186, v187, v149
	v_fma_f32 v148, -v148, v186, v150
	v_div_fmas_f32 v148, v148, v149, v186
	v_div_fixup_f32 v170, v148, v147, 1.0
	v_mul_f32_e32 v150, v146, v170
	v_pk_mul_f32 v[168:169], v[168:169], v[170:171] op_sel_hi:[1,0]
	s_mov_b32 s2, 0x1fffff
	v_lshl_add_u64 v[146:147], s[40:41], 0, v[180:181]
	v_cmp_lt_i32_e32 vcc, s2, v1
	v_lshl_add_u64 v[146:147], v[146:147], 0, v[182:183]
	s_or_b64 s[42:43], vcc, s[42:43]
	s_waitcnt vmcnt(6)
; __device__ __forceinline__ unsigned pk_bf16(float lo, float hi) { const f32x2 v = {lo, hi}; const bf16v2 b = __builtin_convertvector(v, bf16v2); return __builtin_bit_cast(unsigned, b); }
; __device__ __forceinline__ float bf_lo(unsigned u) { return __uint_as_float(u << 16); }
; __device__ __forceinline__ float bf_hi(unsigned u) { return __uint_as_float(u & 0xffff0000u); }
; __device__ __forceinline__ float silu_f(float v) { return v * __builtin_amdgcn_rcpf(1.0f + __builtin_amdgcn_exp2f(-LOG2E * v)); }
; __device__ __forceinline__ int tid_opaque() { int t = threadIdx.x; asm volatile("" : "+v"(t)); return t; }
; __device__ __forceinline__ void dil_combine_phase(const Params& p, int half) {
;     ...
;     for (int idx = blockIdx.x * 512 + tid_opaque(); idx < 16384 * 128; idx += nth) {
;         const int row = idx >> 7, e = (idx & 127) * 8, h = e >> 7;
;         const float l0 = LSE[(size_t)row * 8 + h], l1 = LSE[(size_t)(16384 + row) * 8 + h], l2 = LSE[(size_t)(32768 + row) * 8 + h];
;         const float mx = fmaxf(l0, fmaxf(l1, l2)); float w0 = __builtin_amdgcn_exp2f(l0 - mx), w1 = __builtin_amdgcn_exp2f(l1 - mx), w2 = __builtin_amdgcn_exp2f(l2 - mx);
;         const float inv = 1.0f / (w0 + w1 + w2); w0 *= inv; w1 *= inv; w2 *= inv;
;         const u32x4 a = *(const u32x4*)(OG + (size_t)row * DM + e), b = *(const u32x4*)(OG + (size_t)(16384 + row) * DM + e), c = *(const u32x4*)(OG + (size_t)(32768 + row) * DM + e);
;         const u32x4 z = *(const u32x4*)(PROJ + (size_t)row * 8192 + 7168 + e);
;         u32x4 o;
; #pragma unroll
;         for (int j = 0; j < 4; ++j) {
;             const float lo = (w0 * bf_lo(a[j]) + w1 * bf_lo(b[j]) + w2 * bf_lo(c[j])) * silu_f(bf_lo(z[j]));
;             const float hi = (w0 * bf_hi(a[j]) + w1 * bf_hi(b[j]) + w2 * bf_hi(c[j])) * silu_f(bf_hi(z[j]));
;             o[j] = pk_bf16(lo, hi);
;         }
;         *(u32x4*)(Y + (size_t)row * DM + e) = o;
	v_lshlrev_b32_e32 v178, 16, v160
	v_and_b32_e32 v179, 0xffff0000, v160
	s_waitcnt vmcnt(5)
	v_lshlrev_b32_e32 v170, 16, v164
	v_and_b32_e32 v171, 0xffff0000, v164
	v_mul_f32_e32 v164, 0xbfb8aa3b, v170
	s_waitcnt vmcnt(4)
	v_and_b32_e32 v175, 0xffff0000, v152
	v_lshlrev_b32_e32 v176, 16, v152
	v_mul_f32_e32 v152, 0xbfb8aa3b, v171
	v_exp_f32_e32 v164, v164
	v_exp_f32_e32 v152, v152
	s_waitcnt vmcnt(3)
	v_and_b32_e32 v177, 0xffff0000, v156
	v_lshlrev_b32_e32 v174, 16, v156
	v_add_f32_e32 v164, 1.0, v164
	v_add_f32_e32 v152, 1.0, v152
	v_rcp_f32_e32 v172, v164
	v_rcp_f32_e32 v173, v152
	v_lshlrev_b32_e32 v164, 16, v165
	v_and_b32_e32 v165, 0xffff0000, v165
	v_mul_f32_e32 v156, 0xbfb8aa3b, v164
	v_pk_mul_f32 v[170:171], v[172:173], v[170:171]
	v_pk_mul_f32 v[172:173], v[168:169], v[176:177] op_sel:[1,0] op_sel_hi:[0,1]
	v_pk_fma_f32 v[172:173], v[168:169], v[174:175], v[172:173]
	v_exp_f32_e32 v156, v156
	v_pk_fma_f32 v[172:173], v[150:151], v[178:179], v[172:173] op_sel_hi:[0,1,1]
	v_pk_mul_f32 v[170:171], v[172:173], v[170:171]
	v_lshlrev_b32_e32 v172, 16, v153
	v_cvt_pk_bf16_f32 v152, v170, v171
	v_and_b32_e32 v171, 0xffff0000, v153
	v_mul_f32_e32 v153, 0xbfb8aa3b, v165
	v_exp_f32_e32 v153, v153
	v_add_f32_e32 v156, 1.0, v156
	v_rcp_f32_e32 v156, v156
	v_lshlrev_b32_e32 v170, 16, v157
	v_add_f32_e32 v153, 1.0, v153
	v_and_b32_e32 v173, 0xffff0000, v157
	v_rcp_f32_e32 v157, v153
	v_lshlrev_b32_e32 v160, 16, v161
	v_and_b32_e32 v161, 0xffff0000, v161
	v_pk_mul_f32 v[156:157], v[156:157], v[164:165]
	v_pk_mul_f32 v[164:165], v[168:169], v[172:173] op_sel:[1,0] op_sel_hi:[0,1]
	v_pk_fma_f32 v[164:165], v[168:169], v[170:171], v[164:165]
	v_lshlrev_b32_e32 v170, 16, v154
	v_pk_fma_f32 v[160:161], v[150:151], v[160:161], v[164:165] op_sel_hi:[0,1,1]
	v_pk_mul_f32 v[156:157], v[160:161], v[156:157]
	v_and_b32_e32 v165, 0xffff0000, v154
	v_cvt_pk_bf16_f32 v153, v156, v157
	v_lshlrev_b32_e32 v156, 16, v166
	v_and_b32_e32 v157, 0xffff0000, v166
	v_mul_f32_e32 v160, 0xbfb8aa3b, v156
	v_mul_f32_e32 v154, 0xbfb8aa3b, v157
	v_exp_f32_e32 v160, v160
	v_exp_f32_e32 v154, v154
	v_and_b32_e32 v171, 0xffff0000, v158
	v_lshlrev_b32_e32 v164, 16, v158
	v_add_f32_e32 v160, 1.0, v160
	v_add_f32_e32 v154, 1.0, v154
	v_rcp_f32_e32 v160, v160
	v_rcp_f32_e32 v161, v154
	v_lshlrev_b32_e32 v172, 16, v162
	v_and_b32_e32 v173, 0xffff0000, v162
	v_lshlrev_b32_e32 v162, 16, v163
	v_pk_mul_f32 v[156:157], v[160:161], v[156:157]
	v_pk_mul_f32 v[160:161], v[168:169], v[170:171] op_sel:[1,0] op_sel_hi:[0,1]
	v_pk_fma_f32 v[160:161], v[168:169], v[164:165], v[160:161]
	v_lshlrev_b32_e32 v164, 16, v155
	v_pk_fma_f32 v[160:161], v[150:151], v[172:173], v[160:161] op_sel_hi:[0,1,1]
	v_and_b32_e32 v165, 0xffff0000, v159
	v_pk_mul_f32 v[156:157], v[160:161], v[156:157]
	v_lshlrev_b32_e32 v160, 16, v159
	v_and_b32_e32 v161, 0xffff0000, v155
	v_pk_mul_f32 v[164:165], v[168:169], v[164:165] op_sel:[1,0] op_sel_hi:[0,1]
	v_cvt_pk_bf16_f32 v154, v156, v157
	v_lshlrev_b32_e32 v156, 16, v167
	v_and_b32_e32 v157, 0xffff0000, v167
	v_pk_fma_f32 v[160:161], v[168:169], v[160:161], v[164:165]
	v_and_b32_e32 v163, 0xffff0000, v163
	v_mul_f32_e32 v158, 0xbfb8aa3b, v156
	v_pk_fma_f32 v[160:161], v[150:151], v[162:163], v[160:161] op_sel_hi:[0,1,1]
	v_mul_f32_e32 v150, 0xbfb8aa3b, v157
	v_exp_f32_e32 v158, v158
	v_exp_f32_e32 v150, v150
	v_add_f32_e32 v158, 1.0, v158
	v_add_f32_e32 v150, 1.0, v150
	v_rcp_f32_e32 v158, v158
	v_rcp_f32_e32 v159, v150
	s_nop 0
	v_pk_mul_f32 v[156:157], v[158:159], v[156:157]
	s_nop 0
	v_pk_mul_f32 v[156:157], v[160:161], v[156:157]
	s_nop 0
	v_cvt_pk_bf16_f32 v155, v156, v157
	global_store_dwordx4 v[146:147], v[152:155], off
	s_andn2_b64 exec, exec, s[42:43]
	s_cbranch_execnz .LBB0_68
